# also the XCD-leader path: L1 invalidate behind the cross-XCD arrival atomic instead of between TOPGEN and the XGEN release
# baseline (speedup 1.0000x reference)
.LBB0_69:
	s_andn2_saveexec_b64 s[0:1], s[6:7]
	s_cbranch_execz .LBB0_89
	s_mov_b64 s[6:7], exec
	buffer_wbl2 sc1
	s_waitcnt lgkmcnt(0)
	s_waitcnt vmcnt(0)
	v_mbcnt_lo_u32_b32 v1, s6, 0
	v_mbcnt_hi_u32_b32 v1, s7, v1
	v_cmp_eq_u32_e32 vcc, 0, v1
	s_and_saveexec_b64 s[8:9], vcc
	s_cbranch_execz .LBB0_72
	s_bcnt1_i32_b64 s0, s[6:7]
	v_mov_b32_e32 v2, 0x4000
	v_mov_b32_e32 v3, s0
	global_atomic_add v2, v2, v3, s[92:93] offset:1024 sc0
	buffer_inv sc1

.LBB0_86:
	s_or_b64 exec, exec, s[6:7]
	s_mov_b64 s[6:7], exec
	v_mbcnt_lo_u32_b32 v0, s6, 0
	v_mbcnt_hi_u32_b32 v0, s7, v0
	v_cmp_eq_u32_e32 vcc, 0, v0
	s_waitcnt vmcnt(0)
	s_and_saveexec_b64 s[8:9], vcc
	s_cbranch_execz .LBB0_88
	s_bcnt1_i32_b64 s0, s[6:7]
	v_mov_b32_e32 v0, 0x2000
	v_mov_b32_e32 v1, s0
	global_atomic_add v0, v1, s[4:5] offset:1024

.LBB0_691:
	s_andn2_saveexec_b64 s[0:1], s[8:9]
	s_cbranch_execz .LBB0_711
	s_mov_b64 s[8:9], exec
	buffer_wbl2 sc1
	s_waitcnt lgkmcnt(0)
	s_waitcnt vmcnt(0)
	v_mbcnt_lo_u32_b32 v1, s8, 0
	v_mbcnt_hi_u32_b32 v1, s9, v1
	v_cmp_eq_u32_e32 vcc, 0, v1
	s_and_saveexec_b64 s[10:11], vcc
	s_cbranch_execz .LBB0_694
	s_bcnt1_i32_b64 s0, s[8:9]
	v_mov_b32_e32 v2, 0x4000
	v_mov_b32_e32 v3, s0
	global_atomic_add v2, v2, v3, s[66:67] offset:1024 sc0
	buffer_inv sc1

.LBB0_708:
	s_or_b64 exec, exec, s[8:9]
	s_mov_b64 s[8:9], exec
	v_mbcnt_lo_u32_b32 v0, s8, 0
	v_mbcnt_hi_u32_b32 v0, s9, v0
	v_cmp_eq_u32_e32 vcc, 0, v0
	s_waitcnt vmcnt(0)
	s_and_saveexec_b64 s[10:11], vcc
	s_cbranch_execz .LBB0_710
	s_bcnt1_i32_b64 s0, s[8:9]
	v_mov_b32_e32 v0, 0x2000
	v_mov_b32_e32 v1, s0
	global_atomic_add v0, v1, s[6:7] offset:1024
